# prompt-FoX unit prologue: the bias-table fill issues up to four iterations of its LCUM loads together (was one dependent global load per iteration)
# speedup vs baseline: 1.0065x; 1.0033x over previous
; template <bool NOMAX>
; __device__ __forceinline__ void fox_unit(const AttnCtx& C, int u, LAS unsigned char* lds) {
;     ...
;     const int no = NT - t0o;
;     for (int i = tid; i < no * 64; i += 512) { const int t = t0o + (i >> 6); ckl[i] = (lq0 - DDC(t) - C.LCUM[(size_t)(t * 64 + (i & 63)) * 8 + h]) * LOG2E; }
.LBB0_835:
	v_readlane_b32 s2, v252, 28
	s_waitcnt lgkmcnt(0)
	s_barrier
	v_mov_b32_e32 v5, s2
	ds_read_b32 v5, v5
	s_add_i32 s73, s78, 4
	v_writelane_b32 v253, s10, 56
	s_waitcnt lgkmcnt(0)
	v_readfirstlane_b32 s2, v5
	s_sub_i32 s9, s73, s2
	s_lshl_b32 s10, s9, 6
	v_cmp_gt_i32_e32 vcc, s10, v8
	s_and_saveexec_b64 s[2:3], vcc
	s_cbranch_execz .LBB0_838
	v_readlane_b32 s4, v253, 62
	v_readlane_b32 s5, v253, 63
	s_add_u32 s4, s4, s76
	v_readlane_b32 s6, v253, 32
	s_addc_u32 s5, s5, 0
	v_mov_b32_e32 v11, v8
	v_lshl_add_u32 v6, v8, 2, s6
	s_mov_b64 s[6:7], 0
	v_readfirstlane_b32 s98, v8
	s_sub_i32 s98, s10, s98
	s_add_i32 s98, s98, 0x1ff
	s_lshr_b32 s98, s98, 9
	s_min_u32 s99, s98, 4
	v_mov_b32_e32 v56, v11
	v_ashrrev_i32_e32 v57, 6, v56
	v_add_u32_e32 v57, v57, v5
	v_lshl_or_b32 v58, v57, 6, v212
	v_ashrrev_i32_e32 v59, 31, v58
	v_lshlrev_b64 v[58:59], 5, v[58:59]
	v_lshl_add_u64 v[58:59], s[4:5], 0, v[58:59]
	global_load_dword v60, v[58:59], off
	v_lshl_add_u32 v57, v57, 2, s0
	ds_read_b32 v64, v57
	s_cmp_le_u32 s99, 1
	s_cbranch_scc1 .Lck_issued
	v_add_u32_e32 v56, 0x200, v11
	v_ashrrev_i32_e32 v57, 6, v56
	v_add_u32_e32 v57, v57, v5
	v_lshl_or_b32 v58, v57, 6, v212
	v_ashrrev_i32_e32 v59, 31, v58
	v_lshlrev_b64 v[58:59], 5, v[58:59]
	v_lshl_add_u64 v[58:59], s[4:5], 0, v[58:59]
	global_load_dword v61, v[58:59], off
	v_lshl_add_u32 v57, v57, 2, s0
	ds_read_b32 v65, v57
	s_cmp_le_u32 s99, 2
	s_cbranch_scc1 .Lck_issued
	v_add_u32_e32 v56, 0x400, v11
	v_ashrrev_i32_e32 v57, 6, v56
	v_add_u32_e32 v57, v57, v5
	v_lshl_or_b32 v58, v57, 6, v212
	v_ashrrev_i32_e32 v59, 31, v58
	v_lshlrev_b64 v[58:59], 5, v[58:59]
	v_lshl_add_u64 v[58:59], s[4:5], 0, v[58:59]
	global_load_dword v62, v[58:59], off
	v_lshl_add_u32 v57, v57, 2, s0
	ds_read_b32 v66, v57
	s_cmp_le_u32 s99, 3
	s_cbranch_scc1 .Lck_issued
	v_add_u32_e32 v56, 0x600, v11
	v_ashrrev_i32_e32 v57, 6, v56
	v_add_u32_e32 v57, v57, v5
	v_lshl_or_b32 v58, v57, 6, v212
	v_ashrrev_i32_e32 v59, 31, v58
	v_lshlrev_b64 v[58:59], 5, v[58:59]
	v_lshl_add_u64 v[58:59], s[4:5], 0, v[58:59]
	global_load_dword v63, v[58:59], off
	v_lshl_add_u32 v57, v57, 2, s0
	ds_read_b32 v67, v57
.Lck_issued:
	s_waitcnt vmcnt(0) lgkmcnt(0)
	v_sub_f32_e32 v57, v64, v2
	v_sub_f32_e32 v57, v7, v57
	v_sub_f32_e32 v57, v57, v60
	v_mul_f32_e32 v57, 0x3fb8aa3b, v57
	ds_write_b32 v6, v57
	s_cmp_le_u32 s99, 1
	s_cbranch_scc1 .Lck_done
	v_sub_f32_e32 v57, v65, v2
	v_sub_f32_e32 v57, v7, v57
	v_sub_f32_e32 v57, v57, v61
	v_mul_f32_e32 v57, 0x3fb8aa3b, v57
	ds_write_b32 v6, v57 offset:2048
	s_cmp_le_u32 s99, 2
	s_cbranch_scc1 .Lck_done
	v_sub_f32_e32 v57, v66, v2
	v_sub_f32_e32 v57, v7, v57
	v_sub_f32_e32 v57, v57, v62
	v_mul_f32_e32 v57, 0x3fb8aa3b, v57
	ds_write_b32 v6, v57 offset:4096
	s_cmp_le_u32 s99, 3
	s_cbranch_scc1 .Lck_done
	v_sub_f32_e32 v57, v67, v2
	v_sub_f32_e32 v57, v7, v57
	v_sub_f32_e32 v57, v57, v63
	v_mul_f32_e32 v57, 0x3fb8aa3b, v57
	ds_write_b32 v6, v57 offset:6144
.Lck_done:
	s_lshl_b32 s99, s99, 9
	v_add_u32_e32 v11, s99, v11
	s_lshl_b32 s99, s99, 2
	v_add_u32_e32 v6, s99, v6
	s_cmp_le_u32 s98, 4
	s_cbranch_scc1 .LBB0_838
